# norm loops P1/P7 hand-rewritten: paired rows, all loads up front, DPP reductions
# speedup vs baseline: 1.0032x; 1.0032x over previous
; __device__ __forceinline__ unsigned pk2(float lo, float hi) { unsigned r; asm("v_cvt_pk_bf16_f32 %0, %1, %2" : "=v"(r) : "v"(lo), "v"(hi)); return r; }
; __device__ __forceinline__ void norm_mod_rows(const float* __restrict__ xp, const float* __restrict__ xs, const float* __restrict__ gvec, const float* __restrict__ mod, int ch_shift, int ch_scale, ...
;     for (int r0 = gw; r0 < nrows; r0 += 2 * NGW) {
;         const int r1 = r0 + NGW; const bool two = r1 < nrows;
;         const int gr0 = row_base + r0, gr1 = row_base + (two ? r1 : r0);
;         const float* xrow0 = gr0 < MP ? xp + (size_t)gr0 * DM : xs + (size_t)(gr0 - MP) * DM;
;         const float* xrow1 = gr1 < MP ? xp + (size_t)gr1 * DM : xs + (size_t)(gr1 - MP) * DM;
;         f32x4 v0[4], v1[4]; float s0 = 0.f, s1 = 0.f;
; #pragma unroll
;         for (int j = 0; j < 4; ++j) { v0[j] = ((const f32x4*)xrow0)[lane + 64 * j]; v1[j] = ((const f32x4*)xrow1)[lane + 64 * j]; }
; #pragma unroll
;         for (int j = 0; j < 4; ++j) { s0 += (v0[j][0] * v0[j][0] + v0[j][1] * v0[j][1]) + (v0[j][2] * v0[j][2] + v0[j][3] * v0[j][3]);
;                                       s1 += (v1[j][0] * v1[j][0] + v1[j][1] * v1[j][1]) + (v1[j][2] * v1[j][2] + v1[j][3] * v1[j][3]); }
;         const float rstd0 = rsqrtf(wave_sum(s0) * (1.f / DM) + EPS), rstd1 = rsqrtf(wave_sum(s1) * (1.f / DM) + EPS);
; #pragma unroll
;         for (int q = 0; q < 2; ++q) {
;             if (q == 1 && !two) break;
;             const int gr = q ? gr1 : gr0, r = q ? r1 : r0; const float rstd = q ? rstd1 : rstd0;
;             const int seq = gr < MP ? (gr >> 11) : NPB + ((gr - MP) >> 6);
;             const float* mrow = mod + (size_t)seq * (6 * DM);
;             u32x2* o8 = (u32x2*)(H + (size_t)r * DM);
;             f32x4 gq[4], scq[4], shq[4];
; #pragma unroll
;             for (int j = 0; j < 4; ++j) { const int ci = lane + 64 * j;
;                 gq[j] = ((const f32x4*)gvec)[ci]; scq[j] = ((const f32x4*)(mrow + ch_scale * DM))[ci]; shq[j] = ((const f32x4*)(mrow + ch_shift * DM))[ci]; }
; #pragma unroll
;             for (int j = 0; j < 4; ++j) { const int ci = lane + 64 * j;
;                 const f32x4 y = ((q ? v1[j] : v0[j]) * rstd) * gq[j] * (scq[j] + 1.f) + shq[j];
;                 u32x2 w; w.x = pk2(y[0], y[1]); w.y = pk2(y[2], y[3]); o8[ci] = w; }
.LBB0_139:
	s_lshl_b32 s3, s2, 14
	v_writelane_b32 v255, s3, 31
	s_and_b64 s[4:5], s[6:7], exec
	s_movk_i32 s3, 0x4000
	s_cselect_b32 s3, s3, 0x4800
	v_readlane_b32 s4, v254, 25
	v_mov_b32_e32 v0, v166
	v_writelane_b32 v255, s3, 32
	s_cmp_ge_i32 s4, s3
	v_readlane_b32 s5, v254, 26
	s_cbranch_scc1 .LBB0_144
	v_and_b32_e32 v18, 63, v166
	v_lshlrev_b32_e32 v85, 4, v18
	v_readlane_b32 s14, v255, 7
	v_readlane_b32 s15, v255, 8
	s_nop 4
	global_load_dwordx4 v[2:5], v85, s[14:15]
	global_load_dwordx4 v[6:9], v85, s[14:15] offset:1024
	global_load_dwordx4 v[10:13], v85, s[14:15] offset:2048
	global_load_dwordx4 v[14:17], v85, s[14:15] offset:3072
	v_add_u32_e32 v86, 0x1000, v85
	v_mov_b32_e32 v87, v85
	v_add_u32_e32 v88, 0x1000, v85
	v_lshlrev_b32_e32 v0, 3, v18
	v_readlane_b32 s3, v254, 25
	v_readlane_b32 s5, v252, 4
	v_readlane_b32 s4, v255, 32
	s_lshr_b32 s4, s4, 1
	v_readlane_b32 s8, v255, 31
	s_cmp_ge_i32 s3, s4
	s_cbranch_scc1 .LBB0_144
.Lnorm_loop_p1:
	s_lshl_b32 s9, s3, 1
	s_add_i32 s10, s9, s8
	s_lshl_b32 s22, s9, 11
	s_add_u32 s20, s12, s22
	s_addc_u32 s21, s13, 0
	s_add_i32 s9, s10, 0xffff8000
	s_ashr_i32 s22, s10, 11
	s_lshr_b32 s16, s9, 6
	s_add_i32 s16, s16, 16
	s_cmp_lt_i32 s10, 0x8000
	s_cselect_b32 s14, s30, s34
	s_cselect_b32 s15, s31, s35
	s_cselect_b32 s9, s10, s9
	s_cselect_b32 s22, s22, s16
	s_lshl_b32 s9, s9, 12
	s_add_u32 s14, s14, s9
	s_addc_u32 s15, s15, 0
	s_mul_i32 s22, s22, 0x6000
	v_readlane_b32 s16, v255, 24
	v_readlane_b32 s17, v255, 26
	s_add_u32 s16, s16, s22
	s_addc_u32 s17, s17, 0
	global_load_dwordx4 v[18:21], v85, s[14:15]
	global_load_dwordx4 v[22:25], v85, s[14:15] offset:1024
	global_load_dwordx4 v[26:29], v85, s[14:15] offset:2048
	global_load_dwordx4 v[30:33], v85, s[14:15] offset:3072
	global_load_dwordx4 v[34:37], v86, s[14:15]
	global_load_dwordx4 v[38:41], v86, s[14:15] offset:1024
	global_load_dwordx4 v[42:45], v86, s[14:15] offset:2048
	global_load_dwordx4 v[46:49], v86, s[14:15] offset:3072
	global_load_dwordx4 v[50:53], v88, s[16:17]
	global_load_dwordx4 v[54:57], v88, s[16:17] offset:1024
	global_load_dwordx4 v[58:61], v88, s[16:17] offset:2048
	global_load_dwordx4 v[62:65], v88, s[16:17] offset:3072
	global_load_dwordx4 v[66:69], v87, s[16:17]
	global_load_dwordx4 v[70:73], v87, s[16:17] offset:1024
	global_load_dwordx4 v[74:77], v87, s[16:17] offset:2048
	global_load_dwordx4 v[78:81], v87, s[16:17] offset:3072
	s_waitcnt vmcnt(15)
	v_pk_mul_f32 v[82:83], v[18:19], v[18:19]
	v_pk_fma_f32 v[82:83], v[20:21], v[20:21], v[82:83]
	s_waitcnt vmcnt(14)
	v_pk_fma_f32 v[82:83], v[22:23], v[22:23], v[82:83]
	v_pk_fma_f32 v[82:83], v[24:25], v[24:25], v[82:83]
	s_waitcnt vmcnt(13)
	v_pk_fma_f32 v[82:83], v[26:27], v[26:27], v[82:83]
	v_pk_fma_f32 v[82:83], v[28:29], v[28:29], v[82:83]
	s_waitcnt vmcnt(12)
	v_pk_fma_f32 v[82:83], v[30:31], v[30:31], v[82:83]
	v_pk_fma_f32 v[82:83], v[32:33], v[32:33], v[82:83]
	s_waitcnt vmcnt(11)
	v_pk_mul_f32 v[90:91], v[34:35], v[34:35]
	v_pk_fma_f32 v[90:91], v[36:37], v[36:37], v[90:91]
	s_waitcnt vmcnt(10)
	v_pk_fma_f32 v[90:91], v[38:39], v[38:39], v[90:91]
	v_pk_fma_f32 v[90:91], v[40:41], v[40:41], v[90:91]
	s_waitcnt vmcnt(9)
	v_pk_fma_f32 v[90:91], v[42:43], v[42:43], v[90:91]
	v_pk_fma_f32 v[90:91], v[44:45], v[44:45], v[90:91]
	s_waitcnt vmcnt(8)
	v_pk_fma_f32 v[90:91], v[46:47], v[46:47], v[90:91]
	v_pk_fma_f32 v[90:91], v[48:49], v[48:49], v[90:91]
	s_nop 0
	v_add_f32_e32 v82, v82, v83
	v_add_f32_e32 v90, v90, v91
	s_nop 1
	v_add_f32_dpp v82, v82, v82 quad_perm:[1,0,3,2] row_mask:0xf bank_mask:0xf bound_ctrl:1
	v_add_f32_dpp v90, v90, v90 quad_perm:[1,0,3,2] row_mask:0xf bank_mask:0xf bound_ctrl:1
	s_nop 1
	v_add_f32_dpp v82, v82, v82 quad_perm:[2,3,0,1] row_mask:0xf bank_mask:0xf bound_ctrl:1
	v_add_f32_dpp v90, v90, v90 quad_perm:[2,3,0,1] row_mask:0xf bank_mask:0xf bound_ctrl:1
	s_nop 1
	v_add_f32_dpp v82, v82, v82 row_half_mirror row_mask:0xf bank_mask:0xf bound_ctrl:1
	v_add_f32_dpp v90, v90, v90 row_half_mirror row_mask:0xf bank_mask:0xf bound_ctrl:1
	s_nop 1
	v_add_f32_dpp v82, v82, v82 row_mirror row_mask:0xf bank_mask:0xf bound_ctrl:1
	v_add_f32_dpp v90, v90, v90 row_mirror row_mask:0xf bank_mask:0xf bound_ctrl:1
	s_nop 1
	v_add_f32_dpp v82, v82, v82 row_bcast:15 row_mask:0xa bank_mask:0xf
	v_add_f32_dpp v90, v90, v90 row_bcast:15 row_mask:0xa bank_mask:0xf
	s_nop 1
	v_add_f32_dpp v82, v82, v82 row_bcast:31 row_mask:0xc bank_mask:0xf
	v_add_f32_dpp v90, v90, v90 row_bcast:31 row_mask:0xc bank_mask:0xf
	s_nop 1
	v_readlane_b32 s100, v82, 63
	v_readlane_b32 s101, v90, 63
	s_nop 2
	v_mov_b32_e32 v92, s100
	v_mov_b32_e32 v94, s101
	v_fmamk_f32 v92, v92, 0x3a800000, v167
	v_fmamk_f32 v94, v94, 0x3a800000, v167
	v_rsq_f32_e32 v92, v92
	v_rsq_f32_e32 v94, v94
	s_waitcnt vmcnt(4)
; __device__ __forceinline__ unsigned pk2(float lo, float hi) { unsigned r; asm("v_cvt_pk_bf16_f32 %0, %1, %2" : "=v"(r) : "v"(lo), "v"(hi)); return r; }
; __device__ __forceinline__ void norm_mod_rows(const float* __restrict__ xp, const float* __restrict__ xs, const float* __restrict__ gvec, const float* __restrict__ mod, int ch_shift, int ch_scale, ...
;     ...
; #pragma unroll
;             for (int j = 0; j < 4; ++j) { const int ci = lane + 64 * j;
;                 const f32x4 y = ((q ? v1[j] : v0[j]) * rstd) * gq[j] * (scq[j] + 1.f) + shq[j];
;                 u32x2 w; w.x = pk2(y[0], y[1]); w.y = pk2(y[2], y[3]); o8[ci] = w; }
;         }
	v_pk_add_f32 v[50:51], v[50:51], 1.0 op_sel_hi:[1,0]
	v_pk_add_f32 v[52:53], v[52:53], 1.0 op_sel_hi:[1,0]
	v_pk_add_f32 v[54:55], v[54:55], 1.0 op_sel_hi:[1,0]
	v_pk_add_f32 v[56:57], v[56:57], 1.0 op_sel_hi:[1,0]
	v_pk_add_f32 v[58:59], v[58:59], 1.0 op_sel_hi:[1,0]
	v_pk_add_f32 v[60:61], v[60:61], 1.0 op_sel_hi:[1,0]
	v_pk_add_f32 v[62:63], v[62:63], 1.0 op_sel_hi:[1,0]
	v_pk_add_f32 v[64:65], v[64:65], 1.0 op_sel_hi:[1,0]
	s_waitcnt vmcnt(0)
	v_pk_mul_f32 v[18:19], v[18:19], v[92:93] op_sel_hi:[1,0]
	v_pk_mul_f32 v[20:21], v[20:21], v[92:93] op_sel_hi:[1,0]
	v_pk_mul_f32 v[22:23], v[22:23], v[92:93] op_sel_hi:[1,0]
	v_pk_mul_f32 v[24:25], v[24:25], v[92:93] op_sel_hi:[1,0]
	v_pk_mul_f32 v[26:27], v[26:27], v[92:93] op_sel_hi:[1,0]
	v_pk_mul_f32 v[28:29], v[28:29], v[92:93] op_sel_hi:[1,0]
	v_pk_mul_f32 v[30:31], v[30:31], v[92:93] op_sel_hi:[1,0]
	v_pk_mul_f32 v[32:33], v[32:33], v[92:93] op_sel_hi:[1,0]
	v_pk_mul_f32 v[18:19], v[2:3], v[18:19]
	v_pk_mul_f32 v[20:21], v[4:5], v[20:21]
	v_pk_mul_f32 v[22:23], v[6:7], v[22:23]
	v_pk_mul_f32 v[24:25], v[8:9], v[24:25]
	v_pk_mul_f32 v[26:27], v[10:11], v[26:27]
	v_pk_mul_f32 v[28:29], v[12:13], v[28:29]
	v_pk_mul_f32 v[30:31], v[14:15], v[30:31]
	v_pk_mul_f32 v[32:33], v[16:17], v[32:33]
	v_pk_fma_f32 v[18:19], v[50:51], v[18:19], v[66:67]
	v_pk_fma_f32 v[20:21], v[52:53], v[20:21], v[68:69]
	v_pk_fma_f32 v[22:23], v[54:55], v[22:23], v[70:71]
	v_pk_fma_f32 v[24:25], v[56:57], v[24:25], v[72:73]
	v_pk_fma_f32 v[26:27], v[58:59], v[26:27], v[74:75]
	v_pk_fma_f32 v[28:29], v[60:61], v[28:29], v[76:77]
	v_pk_fma_f32 v[30:31], v[62:63], v[30:31], v[78:79]
	v_pk_fma_f32 v[32:33], v[64:65], v[32:33], v[80:81]
	v_cvt_pk_bf16_f32 v18, v18, v19
	v_cvt_pk_bf16_f32 v19, v20, v21
	v_cvt_pk_bf16_f32 v22, v22, v23
	v_cvt_pk_bf16_f32 v23, v24, v25
	v_cvt_pk_bf16_f32 v26, v26, v27
	v_cvt_pk_bf16_f32 v27, v28, v29
	v_cvt_pk_bf16_f32 v30, v30, v31
	v_cvt_pk_bf16_f32 v31, v32, v33
	global_store_dwordx2 v0, v[18:19], s[20:21]
	global_store_dwordx2 v0, v[22:23], s[20:21] offset:512
	global_store_dwordx2 v0, v[26:27], s[20:21] offset:1024
	global_store_dwordx2 v0, v[30:31], s[20:21] offset:1536
	v_pk_mul_f32 v[34:35], v[34:35], v[94:95] op_sel_hi:[1,0]
	v_pk_mul_f32 v[36:37], v[36:37], v[94:95] op_sel_hi:[1,0]
	v_pk_mul_f32 v[38:39], v[38:39], v[94:95] op_sel_hi:[1,0]
	v_pk_mul_f32 v[40:41], v[40:41], v[94:95] op_sel_hi:[1,0]
	v_pk_mul_f32 v[42:43], v[42:43], v[94:95] op_sel_hi:[1,0]
	v_pk_mul_f32 v[44:45], v[44:45], v[94:95] op_sel_hi:[1,0]
	v_pk_mul_f32 v[46:47], v[46:47], v[94:95] op_sel_hi:[1,0]
	v_pk_mul_f32 v[48:49], v[48:49], v[94:95] op_sel_hi:[1,0]
	v_pk_mul_f32 v[34:35], v[2:3], v[34:35]
	v_pk_mul_f32 v[36:37], v[4:5], v[36:37]
	v_pk_mul_f32 v[38:39], v[6:7], v[38:39]
	v_pk_mul_f32 v[40:41], v[8:9], v[40:41]
	v_pk_mul_f32 v[42:43], v[10:11], v[42:43]
	v_pk_mul_f32 v[44:45], v[12:13], v[44:45]
	v_pk_mul_f32 v[46:47], v[14:15], v[46:47]
	v_pk_mul_f32 v[48:49], v[16:17], v[48:49]
	v_pk_fma_f32 v[34:35], v[50:51], v[34:35], v[66:67]
	v_pk_fma_f32 v[36:37], v[52:53], v[36:37], v[68:69]
	v_pk_fma_f32 v[38:39], v[54:55], v[38:39], v[70:71]
	v_pk_fma_f32 v[40:41], v[56:57], v[40:41], v[72:73]
	v_pk_fma_f32 v[42:43], v[58:59], v[42:43], v[74:75]
	v_pk_fma_f32 v[44:45], v[60:61], v[44:45], v[76:77]
	v_pk_fma_f32 v[46:47], v[62:63], v[46:47], v[78:79]
	v_pk_fma_f32 v[48:49], v[64:65], v[48:49], v[80:81]
	v_cvt_pk_bf16_f32 v34, v34, v35
	v_cvt_pk_bf16_f32 v35, v36, v37
	v_cvt_pk_bf16_f32 v38, v38, v39
	v_cvt_pk_bf16_f32 v39, v40, v41
	v_cvt_pk_bf16_f32 v42, v42, v43
	v_cvt_pk_bf16_f32 v43, v44, v45
	v_cvt_pk_bf16_f32 v46, v46, v47
	v_cvt_pk_bf16_f32 v47, v48, v49
	global_store_dwordx2 v0, v[34:35], s[20:21] offset:2048
	global_store_dwordx2 v0, v[38:39], s[20:21] offset:2560
	global_store_dwordx2 v0, v[42:43], s[20:21] offset:3072
	global_store_dwordx2 v0, v[46:47], s[20:21] offset:3584
	s_add_i32 s3, s3, s5
	s_cmp_lt_i32 s3, s4
	s_cbranch_scc1 .Lnorm_loop_p1

; __device__ __forceinline__ void norm_mod_rows(const float* __restrict__ xp, const float* __restrict__ xs, const float* __restrict__ gvec, const float* __restrict__ mod, int ch_shift, int ch_scale, ...
;     for (int r0 = gw; r0 < nrows; r0 += 2 * NGW) {
;         const int r1 = r0 + NGW; const bool two = r1 < nrows;
;         const int gr0 = row_base + r0, gr1 = row_base + (two ? r1 : r0);
;         const float* xrow0 = gr0 < MP ? xp + (size_t)gr0 * DM : xs + (size_t)(gr0 - MP) * DM;
;         const float* xrow1 = gr1 < MP ? xp + (size_t)gr1 * DM : xs + (size_t)(gr1 - MP) * DM;
;         f32x4 v0[4], v1[4]; float s0 = 0.f, s1 = 0.f;
; #pragma unroll
;         for (int j = 0; j < 4; ++j) { v0[j] = ((const f32x4*)xrow0)[lane + 64 * j]; v1[j] = ((const f32x4*)xrow1)[lane + 64 * j]; }
; #pragma unroll
;         for (int j = 0; j < 4; ++j) { s0 += (v0[j][0] * v0[j][0] + v0[j][1] * v0[j][1]) + (v0[j][2] * v0[j][2] + v0[j][3] * v0[j][3]);
;                                       s1 += (v1[j][0] * v1[j][0] + v1[j][1] * v1[j][1]) + (v1[j][2] * v1[j][2] + v1[j][3] * v1[j][3]); }
;         const float rstd0 = rsqrtf(wave_sum(s0) * (1.f / DM) + EPS), rstd1 = rsqrtf(wave_sum(s1) * (1.f / DM) + EPS);
; #pragma unroll
;         for (int q = 0; q < 2; ++q) {
;             if (q == 1 && !two) break;
;             const int gr = q ? gr1 : gr0, r = q ? r1 : r0; const float rstd = q ? rstd1 : rstd0;
;             const int seq = gr < MP ? (gr >> 11) : NPB + ((gr - MP) >> 6);
;             const float* mrow = mod + (size_t)seq * (6 * DM);
;             u32x2* o8 = (u32x2*)(H + (size_t)r * DM);
;             f32x4 gq[4], scq[4], shq[4];
; #pragma unroll
;             for (int j = 0; j < 4; ++j) { const int ci = lane + 64 * j;
;                 gq[j] = ((const f32x4*)gvec)[ci]; scq[j] = ((const f32x4*)(mrow + ch_scale * DM))[ci]; shq[j] = ((const f32x4*)(mrow + ch_shift * DM))[ci]; }
; #pragma unroll
;             for (int j = 0; j < 4; ++j) { const int ci = lane + 64 * j;
;                 const f32x4 y = ((q ? v1[j] : v0[j]) * rstd) * gq[j] * (scq[j] + 1.f) + shq[j];
;                 u32x2 w; w.x = pk2(y[0], y[1]); w.y = pk2(y[2], y[3]); o8[ci] = w; }
; __global__ void __launch_bounds__(512, 2) mega_fwd(Args a) {
;     ...
;             { OPAQUE_TID(); norm_mod_rows(a.out + O_Y, a.out + O_Y + (size_t)MP * DM, a.in[12] + layer * DM, mod, 3, 4, Hb, 0, MTOT, gw, NGW, tq & 63); }
.LBB0_855:
	v_readlane_b32 s2, v253, 62
	v_readlane_b32 s3, v253, 63
	v_readlane_b32 s34, v255, 0
	v_mov_b32_e32 v0, v166
	s_andn2_b64 vcc, exec, s[2:3]
	v_readlane_b32 s35, v255, 1
	s_cbranch_vccnz .LBB0_860
	v_and_b32_e32 v18, 63, v166
	v_lshlrev_b32_e32 v85, 4, v18
	v_readlane_b32 s14, v255, 5
	v_readlane_b32 s15, v255, 6
	v_readlane_b32 s16, v252, 13
	v_readlane_b32 s17, v252, 14
	s_add_u32 s14, s16, s14
	s_addc_u32 s15, s17, s15
	s_nop 4
	global_load_dwordx4 v[2:5], v85, s[14:15]
	global_load_dwordx4 v[6:9], v85, s[14:15] offset:1024
	global_load_dwordx4 v[10:13], v85, s[14:15] offset:2048
	global_load_dwordx4 v[14:17], v85, s[14:15] offset:3072
	v_add_u32_e32 v86, 0x1000, v85
	v_add_u32_e32 v87, 0x3000, v85
	v_add_u32_e32 v88, 0x4000, v85
	v_lshlrev_b32_e32 v0, 3, v18
	v_readlane_b32 s3, v254, 25
	v_readlane_b32 s5, v252, 4
	s_movk_i32 s4, 0x4400
	s_mov_b32 s8, 0
	s_cmp_ge_i32 s3, s4
	s_cbranch_scc1 .LBB0_860
.Lnorm_loop_p7:
	s_lshl_b32 s9, s3, 1
	s_add_i32 s10, s9, s8
	s_lshl_b32 s22, s9, 11
	s_add_u32 s20, s12, s22
	s_addc_u32 s21, s13, 0
	s_add_i32 s9, s10, 0xffff8000
	s_ashr_i32 s22, s10, 11
	s_lshr_b32 s16, s9, 6
	s_add_i32 s16, s16, 16
	s_cmp_lt_i32 s10, 0x8000
	s_cselect_b32 s14, s24, s34
	s_cselect_b32 s15, s25, s35
	s_cselect_b32 s9, s10, s9
	s_cselect_b32 s22, s22, s16
	s_lshl_b32 s9, s9, 12
	s_add_u32 s14, s14, s9
	s_addc_u32 s15, s15, 0
	s_mul_i32 s22, s22, 0x6000
	v_readlane_b32 s16, v255, 24
	v_readlane_b32 s17, v255, 26
	s_add_u32 s16, s16, s22
	s_addc_u32 s17, s17, 0
	global_load_dwordx4 v[18:21], v85, s[14:15]
	global_load_dwordx4 v[22:25], v85, s[14:15] offset:1024
	global_load_dwordx4 v[26:29], v85, s[14:15] offset:2048
	global_load_dwordx4 v[30:33], v85, s[14:15] offset:3072
	global_load_dwordx4 v[34:37], v86, s[14:15]
	global_load_dwordx4 v[38:41], v86, s[14:15] offset:1024
	global_load_dwordx4 v[42:45], v86, s[14:15] offset:2048
	global_load_dwordx4 v[46:49], v86, s[14:15] offset:3072
	global_load_dwordx4 v[50:53], v88, s[16:17]
	global_load_dwordx4 v[54:57], v88, s[16:17] offset:1024
	global_load_dwordx4 v[58:61], v88, s[16:17] offset:2048
	global_load_dwordx4 v[62:65], v88, s[16:17] offset:3072
	global_load_dwordx4 v[66:69], v87, s[16:17]
	global_load_dwordx4 v[70:73], v87, s[16:17] offset:1024
	global_load_dwordx4 v[74:77], v87, s[16:17] offset:2048
	global_load_dwordx4 v[78:81], v87, s[16:17] offset:3072
	s_waitcnt vmcnt(15)
	v_pk_mul_f32 v[82:83], v[18:19], v[18:19]
	v_pk_fma_f32 v[82:83], v[20:21], v[20:21], v[82:83]
	s_waitcnt vmcnt(14)
	v_pk_fma_f32 v[82:83], v[22:23], v[22:23], v[82:83]
	v_pk_fma_f32 v[82:83], v[24:25], v[24:25], v[82:83]
	s_waitcnt vmcnt(13)
	v_pk_fma_f32 v[82:83], v[26:27], v[26:27], v[82:83]
	v_pk_fma_f32 v[82:83], v[28:29], v[28:29], v[82:83]
	s_waitcnt vmcnt(12)
	v_pk_fma_f32 v[82:83], v[30:31], v[30:31], v[82:83]
	v_pk_fma_f32 v[82:83], v[32:33], v[32:33], v[82:83]
	s_waitcnt vmcnt(11)
	v_pk_mul_f32 v[90:91], v[34:35], v[34:35]
	v_pk_fma_f32 v[90:91], v[36:37], v[36:37], v[90:91]
	s_waitcnt vmcnt(10)
	v_pk_fma_f32 v[90:91], v[38:39], v[38:39], v[90:91]
	v_pk_fma_f32 v[90:91], v[40:41], v[40:41], v[90:91]
	s_waitcnt vmcnt(9)
	v_pk_fma_f32 v[90:91], v[42:43], v[42:43], v[90:91]
	v_pk_fma_f32 v[90:91], v[44:45], v[44:45], v[90:91]
	s_waitcnt vmcnt(8)
	v_pk_fma_f32 v[90:91], v[46:47], v[46:47], v[90:91]
	v_pk_fma_f32 v[90:91], v[48:49], v[48:49], v[90:91]
	s_nop 0
	v_add_f32_e32 v82, v82, v83
	v_add_f32_e32 v90, v90, v91
	s_nop 1
	v_add_f32_dpp v82, v82, v82 quad_perm:[1,0,3,2] row_mask:0xf bank_mask:0xf bound_ctrl:1
	v_add_f32_dpp v90, v90, v90 quad_perm:[1,0,3,2] row_mask:0xf bank_mask:0xf bound_ctrl:1
	s_nop 1
	v_add_f32_dpp v82, v82, v82 quad_perm:[2,3,0,1] row_mask:0xf bank_mask:0xf bound_ctrl:1
	v_add_f32_dpp v90, v90, v90 quad_perm:[2,3,0,1] row_mask:0xf bank_mask:0xf bound_ctrl:1
	s_nop 1
	v_add_f32_dpp v82, v82, v82 row_half_mirror row_mask:0xf bank_mask:0xf bound_ctrl:1
	v_add_f32_dpp v90, v90, v90 row_half_mirror row_mask:0xf bank_mask:0xf bound_ctrl:1
	s_nop 1
	v_add_f32_dpp v82, v82, v82 row_mirror row_mask:0xf bank_mask:0xf bound_ctrl:1
	v_add_f32_dpp v90, v90, v90 row_mirror row_mask:0xf bank_mask:0xf bound_ctrl:1
	s_nop 1
	v_add_f32_dpp v82, v82, v82 row_bcast:15 row_mask:0xa bank_mask:0xf
	v_add_f32_dpp v90, v90, v90 row_bcast:15 row_mask:0xa bank_mask:0xf
	s_nop 1
	v_add_f32_dpp v82, v82, v82 row_bcast:31 row_mask:0xc bank_mask:0xf
	v_add_f32_dpp v90, v90, v90 row_bcast:31 row_mask:0xc bank_mask:0xf
	s_nop 1
	v_readlane_b32 s100, v82, 63
	v_readlane_b32 s101, v90, 63
	s_nop 2
	v_mov_b32_e32 v92, s100
	v_mov_b32_e32 v94, s101
	v_fmamk_f32 v92, v92, 0x3a800000, v167
	v_fmamk_f32 v94, v94, 0x3a800000, v167
	v_rsq_f32_e32 v92, v92
	v_rsq_f32_e32 v94, v94
	s_waitcnt vmcnt(4)
; __device__ __forceinline__ unsigned pk2(float lo, float hi) { unsigned r; asm("v_cvt_pk_bf16_f32 %0, %1, %2" : "=v"(r) : "v"(lo), "v"(hi)); return r; }
; __device__ __forceinline__ void norm_mod_rows(const float* __restrict__ xp, const float* __restrict__ xs, const float* __restrict__ gvec, const float* __restrict__ mod, int ch_shift, int ch_scale, ...
;     ...
; #pragma unroll
;             for (int j = 0; j < 4; ++j) { const int ci = lane + 64 * j;
;                 const f32x4 y = ((q ? v1[j] : v0[j]) * rstd) * gq[j] * (scq[j] + 1.f) + shq[j];
;                 u32x2 w; w.x = pk2(y[0], y[1]); w.y = pk2(y[2], y[3]); o8[ci] = w; }
;         }
	v_pk_add_f32 v[50:51], v[50:51], 1.0 op_sel_hi:[1,0]
	v_pk_add_f32 v[52:53], v[52:53], 1.0 op_sel_hi:[1,0]
	v_pk_add_f32 v[54:55], v[54:55], 1.0 op_sel_hi:[1,0]
	v_pk_add_f32 v[56:57], v[56:57], 1.0 op_sel_hi:[1,0]
	v_pk_add_f32 v[58:59], v[58:59], 1.0 op_sel_hi:[1,0]
	v_pk_add_f32 v[60:61], v[60:61], 1.0 op_sel_hi:[1,0]
	v_pk_add_f32 v[62:63], v[62:63], 1.0 op_sel_hi:[1,0]
	v_pk_add_f32 v[64:65], v[64:65], 1.0 op_sel_hi:[1,0]
	s_waitcnt vmcnt(0)
	v_pk_mul_f32 v[18:19], v[18:19], v[92:93] op_sel_hi:[1,0]
	v_pk_mul_f32 v[20:21], v[20:21], v[92:93] op_sel_hi:[1,0]
	v_pk_mul_f32 v[22:23], v[22:23], v[92:93] op_sel_hi:[1,0]
	v_pk_mul_f32 v[24:25], v[24:25], v[92:93] op_sel_hi:[1,0]
	v_pk_mul_f32 v[26:27], v[26:27], v[92:93] op_sel_hi:[1,0]
	v_pk_mul_f32 v[28:29], v[28:29], v[92:93] op_sel_hi:[1,0]
	v_pk_mul_f32 v[30:31], v[30:31], v[92:93] op_sel_hi:[1,0]
	v_pk_mul_f32 v[32:33], v[32:33], v[92:93] op_sel_hi:[1,0]
	v_pk_mul_f32 v[18:19], v[2:3], v[18:19]
	v_pk_mul_f32 v[20:21], v[4:5], v[20:21]
	v_pk_mul_f32 v[22:23], v[6:7], v[22:23]
	v_pk_mul_f32 v[24:25], v[8:9], v[24:25]
	v_pk_mul_f32 v[26:27], v[10:11], v[26:27]
	v_pk_mul_f32 v[28:29], v[12:13], v[28:29]
	v_pk_mul_f32 v[30:31], v[14:15], v[30:31]
	v_pk_mul_f32 v[32:33], v[16:17], v[32:33]
	v_pk_fma_f32 v[18:19], v[50:51], v[18:19], v[66:67]
	v_pk_fma_f32 v[20:21], v[52:53], v[20:21], v[68:69]
	v_pk_fma_f32 v[22:23], v[54:55], v[22:23], v[70:71]
	v_pk_fma_f32 v[24:25], v[56:57], v[24:25], v[72:73]
	v_pk_fma_f32 v[26:27], v[58:59], v[26:27], v[74:75]
	v_pk_fma_f32 v[28:29], v[60:61], v[28:29], v[76:77]
	v_pk_fma_f32 v[30:31], v[62:63], v[30:31], v[78:79]
	v_pk_fma_f32 v[32:33], v[64:65], v[32:33], v[80:81]
	v_cvt_pk_bf16_f32 v18, v18, v19
	v_cvt_pk_bf16_f32 v19, v20, v21
	v_cvt_pk_bf16_f32 v22, v22, v23
	v_cvt_pk_bf16_f32 v23, v24, v25
	v_cvt_pk_bf16_f32 v26, v26, v27
	v_cvt_pk_bf16_f32 v27, v28, v29
	v_cvt_pk_bf16_f32 v30, v30, v31
	v_cvt_pk_bf16_f32 v31, v32, v33
	global_store_dwordx2 v0, v[18:19], s[20:21]
	global_store_dwordx2 v0, v[22:23], s[20:21] offset:512
	global_store_dwordx2 v0, v[26:27], s[20:21] offset:1024
	global_store_dwordx2 v0, v[30:31], s[20:21] offset:1536
	v_pk_mul_f32 v[34:35], v[34:35], v[94:95] op_sel_hi:[1,0]
	v_pk_mul_f32 v[36:37], v[36:37], v[94:95] op_sel_hi:[1,0]
	v_pk_mul_f32 v[38:39], v[38:39], v[94:95] op_sel_hi:[1,0]
	v_pk_mul_f32 v[40:41], v[40:41], v[94:95] op_sel_hi:[1,0]
	v_pk_mul_f32 v[42:43], v[42:43], v[94:95] op_sel_hi:[1,0]
	v_pk_mul_f32 v[44:45], v[44:45], v[94:95] op_sel_hi:[1,0]
	v_pk_mul_f32 v[46:47], v[46:47], v[94:95] op_sel_hi:[1,0]
	v_pk_mul_f32 v[48:49], v[48:49], v[94:95] op_sel_hi:[1,0]
	v_pk_mul_f32 v[34:35], v[2:3], v[34:35]
	v_pk_mul_f32 v[36:37], v[4:5], v[36:37]
	v_pk_mul_f32 v[38:39], v[6:7], v[38:39]
	v_pk_mul_f32 v[40:41], v[8:9], v[40:41]
	v_pk_mul_f32 v[42:43], v[10:11], v[42:43]
	v_pk_mul_f32 v[44:45], v[12:13], v[44:45]
	v_pk_mul_f32 v[46:47], v[14:15], v[46:47]
	v_pk_mul_f32 v[48:49], v[16:17], v[48:49]
	v_pk_fma_f32 v[34:35], v[50:51], v[34:35], v[66:67]
	v_pk_fma_f32 v[36:37], v[52:53], v[36:37], v[68:69]
	v_pk_fma_f32 v[38:39], v[54:55], v[38:39], v[70:71]
	v_pk_fma_f32 v[40:41], v[56:57], v[40:41], v[72:73]
	v_pk_fma_f32 v[42:43], v[58:59], v[42:43], v[74:75]
	v_pk_fma_f32 v[44:45], v[60:61], v[44:45], v[76:77]
	v_pk_fma_f32 v[46:47], v[62:63], v[46:47], v[78:79]
	v_pk_fma_f32 v[48:49], v[64:65], v[48:49], v[80:81]
	v_cvt_pk_bf16_f32 v34, v34, v35
	v_cvt_pk_bf16_f32 v35, v36, v37
	v_cvt_pk_bf16_f32 v38, v38, v39
	v_cvt_pk_bf16_f32 v39, v40, v41
	v_cvt_pk_bf16_f32 v42, v42, v43
	v_cvt_pk_bf16_f32 v43, v44, v45
	v_cvt_pk_bf16_f32 v46, v46, v47
	v_cvt_pk_bf16_f32 v47, v48, v49
	global_store_dwordx2 v0, v[34:35], s[20:21] offset:2048
	global_store_dwordx2 v0, v[38:39], s[20:21] offset:2560
	global_store_dwordx2 v0, v[42:43], s[20:21] offset:3072
	global_store_dwordx2 v0, v[46:47], s[20:21] offset:3584
	s_add_i32 s3, s3, s5
	s_cmp_lt_i32 s3, s4
	s_cbranch_scc1 .Lnorm_loop_p7

; __global__ void __launch_bounds__(512, 2) mega_fwd(Args a) {
	.amdhsa_kernel _Z8mega_fwd4Args
		.amdhsa_group_segment_fixed_size 0
		.amdhsa_private_segment_fixed_size 0
		.amdhsa_kernarg_size 496
		.amdhsa_user_sgpr_count 2
		.amdhsa_user_sgpr_dispatch_ptr 0
		.amdhsa_user_sgpr_queue_ptr 0
		.amdhsa_user_sgpr_kernarg_segment_ptr 1
		.amdhsa_user_sgpr_dispatch_id 0
		.amdhsa_user_sgpr_kernarg_preload_length 0
		.amdhsa_user_sgpr_kernarg_preload_offset 0
		.amdhsa_user_sgpr_private_segment_size 0
		.amdhsa_uses_dynamic_stack 0
		.amdhsa_enable_private_segment 0
		.amdhsa_system_sgpr_workgroup_id_x 1
		.amdhsa_system_sgpr_workgroup_id_y 0
		.amdhsa_system_sgpr_workgroup_id_z 0
		.amdhsa_system_sgpr_workgroup_info 0
		.amdhsa_system_vgpr_workitem_id 2
		.amdhsa_next_free_vgpr 256
		.amdhsa_next_free_sgpr 102
		.amdhsa_accum_offset 256
		.amdhsa_reserve_vcc 1
		.amdhsa_float_round_mode_32 0
		.amdhsa_float_round_mode_16_64 0
		.amdhsa_float_denorm_mode_32 3
		.amdhsa_float_denorm_mode_16_64 3
		.amdhsa_dx10_clamp 1
		.amdhsa_ieee_mode 1
		.amdhsa_fp16_overflow 0
		.amdhsa_tg_split 0
		.amdhsa_exception_fp_ieee_invalid_op 0
		.amdhsa_exception_fp_denorm_src 0
		.amdhsa_exception_fp_ieee_div_zero 0
		.amdhsa_exception_fp_ieee_overflow 0
		.amdhsa_exception_fp_ieee_underflow 0
		.amdhsa_exception_fp_ieee_inexact 0
		.amdhsa_exception_int_div_zero 0
	.end_amdhsa_kernel

; __global__ void __launch_bounds__(512, 2) mega_fwd(Args a) {
amdhsa.kernels:
  - .agpr_count:     0
    .args:
      - .offset:         0
        .size:           240
        .value_kind:     by_value
      - .offset:         240
        .size:           4
        .value_kind:     hidden_block_count_x
      - .offset:         244
        .size:           4
        .value_kind:     hidden_block_count_y
      - .offset:         248
        .size:           4
        .value_kind:     hidden_block_count_z
      - .offset:         252
        .size:           2
        .value_kind:     hidden_group_size_x
      - .offset:         254
        .size:           2
        .value_kind:     hidden_group_size_y
      - .offset:         256
        .size:           2
        .value_kind:     hidden_group_size_z
      - .offset:         258
        .size:           2
        .value_kind:     hidden_remainder_x
      - .offset:         260
        .size:           2
        .value_kind:     hidden_remainder_y
      - .offset:         262
        .size:           2
        .value_kind:     hidden_remainder_z
      - .offset:         280
        .size:           8
        .value_kind:     hidden_global_offset_x
      - .offset:         288
        .size:           8
        .value_kind:     hidden_global_offset_y
      - .offset:         296
        .size:           8
        .value_kind:     hidden_global_offset_z
      - .offset:         304
        .size:           2
        .value_kind:     hidden_grid_dims
      - .offset:         328
        .size:           8
        .value_kind:     hidden_multigrid_sync_arg
      - .offset:         360
        .size:           4
        .value_kind:     hidden_dynamic_lds_size
    .group_segment_fixed_size: 0
    .kernarg_segment_align: 8
    .kernarg_segment_size: 496
    .language:       OpenCL C
    .language_version:
      - 2
      - 0
    .max_flat_workgroup_size: 512
    .name:           _Z8mega_fwd4Args
    .private_segment_fixed_size: 0
    .sgpr_count:     108
    .sgpr_spill_count: 234
    .symbol:         _Z8mega_fwd4Args.kd
    .uniform_work_group_size: 1
    .uses_dynamic_stack: false
    .vgpr_count:     256
    .vgpr_spill_count: 0
    .wavefront_size: 64
